# gdnpre K.Q / K.K chunk products: B fragments read ahead into spare VGPR quads with counted lgkmcnt (on top of the gemm_out loop change)
# speedup vs baseline: 1.0051x; 1.0051x over previous
.LBB0_243:
	s_or_b64 exec, exec, s[12:13]
	v_and_b32_e32 v37, 15, v1
	v_lshlrev_b32_e32 v43, 4, v68
	v_and_b32_e32 v3, 48, v34
	v_or_b32_e32 v2, v43, v37
	v_add_u32_e32 v42, 0, v3
	s_waitcnt lgkmcnt(0)
	s_barrier
	v_mad_u64_u32 v[40:41], s[0:1], v2, s39, v[42:43]
	ds_read_b128 v[2:5], v40 offset:33280
	v_mul_u32_u24_e32 v6, 0x48, v37
	v_lshl_add_u32 v35, v6, 1, v42
	ds_read_b128 v[152:155], v35 offset:42496
	ds_read_b128 v[156:159], v35 offset:33280
	ds_read_b128 v[160:163], v35 offset:44800
	ds_read_b128 v[164:167], v35 offset:35584
	ds_read_b128 v[168:171], v35 offset:47104
	ds_read_b128 v[234:237], v35 offset:37888
	ds_read_b128 v[238:241], v35 offset:49408
	ds_read_b128 v[250:253], v35 offset:40192
	s_nop 0
	s_nop 0
	s_nop 0
	s_nop 0
	s_nop 0
	s_nop 0
	s_nop 0
	s_waitcnt lgkmcnt(3)
	v_mfma_f32_16x16x32_bf16 v[46:49], v[2:5], v[168:171], 0
	ds_read_b128 v[168:171], v35 offset:42560
	s_add_i32 s2, 0, 0x11200
	v_lshlrev_b32_e32 v41, 2, v37
	s_add_i32 s11, 0, 0x11400
	s_nop 0
	s_waitcnt lgkmcnt(3)
	v_mfma_f32_16x16x32_bf16 v[50:53], v[2:5], v[234:237], 0
	ds_read_b128 v[234:237], v35 offset:33344
	s_nop 0
	s_nop 0
	v_lshrrev_b32_e32 v45, 4, v34
	v_lshl_or_b32 v44, v45, 2, v43
	v_mfma_f32_16x16x32_bf16 v[6:9], v[2:5], v[152:155], 0
	ds_read_b128 v[152:155], v35 offset:44864
	v_cmp_lt_i32_e64 s[40:41], v37, v44
	v_cmp_ge_i32_e64 s[0:1], v37, v44
	v_mfma_f32_16x16x32_bf16 v[10:13], v[2:5], v[156:159], 0
	ds_read_b128 v[156:159], v35 offset:35648
	v_mfma_f32_16x16x32_bf16 v[14:17], v[2:5], v[160:163], 0
	ds_read_b128 v[160:163], v35 offset:47168
	v_mfma_f32_16x16x32_bf16 v[18:21], v[2:5], v[164:167], 0
	s_nop 0
	s_waitcnt lgkmcnt(6)
	v_mfma_f32_16x16x32_bf16 v[54:57], v[2:5], v[238:241], 0
	s_nop 0
	s_waitcnt lgkmcnt(5)
	v_mfma_f32_16x16x32_bf16 v[2:5], v[2:5], v[250:253], 0
	ds_read_b128 v[58:61], v40 offset:33344
	s_nop 0
	s_nop 0
	s_nop 0
	s_waitcnt lgkmcnt(0)
	v_mfma_f32_16x16x32_bf16 v[30:33], v[58:61], v[168:171], v[6:9]
	s_nop 0
	v_mfma_f32_16x16x32_bf16 v[26:29], v[58:61], v[234:237], v[10:13]
	s_nop 0
	s_nop 0
	s_nop 0
	s_nop 0
	s_nop 0
	v_mfma_f32_16x16x32_bf16 v[22:25], v[58:61], v[152:155], v[14:17]
	s_nop 0
	v_mfma_f32_16x16x32_bf16 v[18:21], v[58:61], v[156:159], v[18:21]
	s_nop 0
	ds_read_b128 v[10:13], v35 offset:37952
	s_nop 0
	v_mfma_f32_16x16x32_bf16 v[14:17], v[58:61], v[160:163], v[46:49]
	ds_read_b128 v[6:9], v35 offset:49472
	s_nop 1
	ds_read_b128 v[46:49], v35 offset:40256
	v_add_u32_e32 v35, s2, v41
	s_waitcnt lgkmcnt(0)
	s_barrier
	s_waitcnt lgkmcnt(0)
	v_mfma_f32_16x16x32_bf16 v[2:5], v[58:61], v[46:49], v[2:5]
	v_add_u32_e32 v47, s11, v41
	ds_read_b32 v39, v35
	v_mfma_f32_16x16x32_bf16 v[6:9], v[58:61], v[6:9], v[54:57]
	s_nop 2
	ds_read_b32 v57, v47
	v_or_b32_e32 v35, 0x100, v41
	v_mfma_f32_16x16x32_bf16 v[10:13], v[58:61], v[10:13], v[50:53]
	v_add_u32_e32 v46, s2, v35
	v_add_u32_e32 v35, s11, v35
	ds_read_b32 v46, v46
	ds_read_b32 v58, v35
	v_lshl_add_u32 v51, v44, 2, s2
	ds_read_b32 v35, v51 offset:256
	v_mov_b32_e32 v47, 0
	v_mov_b32_e32 v61, 0
	s_and_saveexec_b64 s[12:13], s[0:1]
	s_cbranch_execz .LBB0_245
	ds_read_b32 v48, v51
	s_waitcnt lgkmcnt(0)
	v_sub_f32_e32 v48, v39, v48
	v_mul_f32_e32 v48, 0x3fb8aa3b, v48
	v_exp_f32_e32 v61, v48
